# attnB loop: waves 4-7 run half an iteration behind waves 0-3 (their per-iteration barrier sits after the 12th MFMA)
# baseline (speedup 1.0000x reference)
; __device__ __forceinline__ void attnB_unit(LAS unsigned char* lds, const unsigned char* ws, int unit, float lam, const float* subln_g) {
;     ...
;     const bf16* kg = KB + (rowb + lane) * 512 + hd * 128 + wid * 8;
;     const bf16* vg0 = VB + (rowb + (wid & 3) * 16 + (lane >> 2)) * 512 + hd * 128 + (wid >> 2) * 32 + (lane & 3) * 8;
;     const unsigned ldsb = (unsigned)(unsigned long)lds;
;     const unsigned kd = ldsb + wid * BK_CH, vd0 = ldsb + 2 * BK_IMG + (wid >> 2) * BV_DB + (wid & 3) * 1024;
.LBB0_296:
	v_add_u32_e32 v150, 0x10400, v146
	v_add_u32_e32 v151, 0x10400, v147
	v_add_u32_e32 v152, 0x10400, v148
	v_add_u32_e32 v153, 0x10400, v149
	s_mov_b32 s8, s24
	s_and_b32 s9, s25, 0xffff
	s_mov_b32 s10, -1
	s_mov_b32 s11, 0x20000
	s_mov_b32 s12, s26
	s_and_b32 s13, s27, 0xffff
	s_mov_b32 s14, -1
	s_mov_b32 s15, 0x20000
	v_subrev_u32_e32 v250, s24, v174
	v_subrev_u32_e32 v251, s26, v176
	s_add_i32 s0, s50, 0xffff0000
	s_and_b32 s0, s0, 0x1f8000
	s_lshl_b32 s4, s0, 1
	s_add_i32 m0, s41, 0x10400
	s_nop 0
	buffer_load_dwordx4 v250, s[8:11], s4 offen lds
	s_add_i32 m0, s41, 0x12400
	s_nop 0
	buffer_load_dwordx4 v250, s[8:11], s4 offen offset:128 lds
	s_add_i32 m0, s43, 0x10400
	s_nop 0
	buffer_load_dwordx4 v251, s[12:15], s4 offen lds
	s_add_i32 m0, s43, 0x12400
	s_nop 0
	buffer_load_dwordx4 v251, s[12:15], s4 offen offset:128 lds
	ds_read_b64_tr_b16 v[192:193], v179 offset:16640
	ds_read_b64_tr_b16 v[194:195], v179 offset:17152
	ds_read_b64_tr_b16 v[196:197], v179 offset:20800
	ds_read_b64_tr_b16 v[198:199], v179 offset:21312
	ds_read_b64_tr_b16 v[200:201], v179 offset:24960
	ds_read_b64_tr_b16 v[202:203], v179 offset:25472
	ds_read_b64_tr_b16 v[204:205], v179 offset:29120
	ds_read_b64_tr_b16 v[206:207], v179 offset:29632
	ds_read_b64_tr_b16 v[208:209], v179 offset:17664
	ds_read_b64_tr_b16 v[210:211], v179 offset:18176
	ds_read_b64_tr_b16 v[212:213], v179 offset:21824
	ds_read_b64_tr_b16 v[214:215], v179 offset:22336
	ds_read_b64_tr_b16 v[216:217], v179 offset:25984
	ds_read_b64_tr_b16 v[218:219], v179 offset:26496
	ds_read_b64_tr_b16 v[220:221], v179 offset:30144
	ds_read_b64_tr_b16 v[222:223], v179 offset:30656
	v_exp_f32_e32 v240, v112
	v_exp_f32_e32 v241, v113
	v_exp_f32_e32 v242, v114
	v_exp_f32_e32 v243, v115
	v_exp_f32_e32 v244, v116
	v_exp_f32_e32 v245, v117
	v_add_f32_e32 v145, v240, v241
	v_cvt_pk_bf16_f32 v224, v240, v241
	v_exp_f32_e32 v246, v118
	v_exp_f32_e32 v247, v119
	v_add_f32_e32 v145, v145, v242
	v_add_f32_e32 v145, v145, v243
	v_cvt_pk_bf16_f32 v225, v242, v243
	v_exp_f32_e32 v240, v120
	v_exp_f32_e32 v241, v121
	v_add_f32_e32 v145, v145, v244
	v_add_f32_e32 v145, v145, v245
	v_cvt_pk_bf16_f32 v226, v244, v245
	v_exp_f32_e32 v242, v122
	v_exp_f32_e32 v243, v123
	v_add_f32_e32 v145, v145, v246
	v_add_f32_e32 v145, v145, v247
	v_cvt_pk_bf16_f32 v227, v246, v247
	v_exp_f32_e32 v244, v124
	v_exp_f32_e32 v245, v125
	v_add_f32_e32 v145, v145, v240
	v_add_f32_e32 v145, v145, v241
	v_cvt_pk_bf16_f32 v228, v240, v241
	v_exp_f32_e32 v246, v126
	v_exp_f32_e32 v247, v127
	v_add_f32_e32 v145, v145, v242
	v_add_f32_e32 v145, v145, v243
	v_cvt_pk_bf16_f32 v229, v242, v243
	v_add_f32_e32 v145, v145, v244
	v_add_f32_e32 v145, v145, v245
	v_cvt_pk_bf16_f32 v230, v244, v245
	v_add_f32_e32 v145, v145, v246
	v_add_f32_e32 v248, v145, v247
	v_cvt_pk_bf16_f32 v231, v246, v247
	s_cmp_lg_u32 s40, 0
	s_cbranch_scc1 .Lb_loopB

.Lb_loopB:
	s_waitcnt lgkmcnt(0)
	v_mfma_f32_32x32x16_bf16 v[32:47], v[192:195], v[224:227], v[32:47]
	v_mfma_f32_32x32x16_bf16 v[48:63], v[196:199], v[224:227], v[48:63]
	ds_read_b128 v[96:99], v146 offset:33280
	ds_read_b128 v[100:103], v147 offset:33280
	ds_read_b128 v[104:107], v148 offset:33280
	ds_read_b128 v[108:111], v149 offset:33280
	v_mfma_f32_32x32x16_bf16 v[16:31], v[200:203], v[224:227], v[16:31]
	v_exp_f32_e32 v240, v80
	v_exp_f32_e32 v241, v81
	v_exp_f32_e32 v242, v82
	v_mfma_f32_32x32x16_bf16 v[0:15], v[204:207], v[224:227], v[0:15]
	v_exp_f32_e32 v243, v83
	v_exp_f32_e32 v244, v84
	v_exp_f32_e32 v245, v85
	s_waitcnt lgkmcnt(0)
	v_mfma_f32_32x32x16_bf16 v[112:127], v[96:99], v[128:131], v[64:79]
	ds_read_b128 v[96:99], v146 offset:37376
	ds_read_b64_tr_b16 v[192:193], v179 offset:18688
	ds_read_b64_tr_b16 v[194:195], v179 offset:19200
	v_add_f32_e32 v145, v240, v241
	v_cvt_pk_bf16_f32 v232, v240, v241
	v_exp_f32_e32 v246, v86
	v_exp_f32_e32 v247, v87
	v_mfma_f32_32x32x16_bf16 v[112:127], v[100:103], v[132:135], v[112:127]
	ds_read_b128 v[100:103], v147 offset:37376
	ds_read_b64_tr_b16 v[196:197], v179 offset:22848
	ds_read_b64_tr_b16 v[198:199], v179 offset:23360
	s_add_i32 s0, s50, 0xffff8000
	s_and_b32 s0, s0, 0x1f8000
	s_lshl_b32 s4, s0, 1
	s_add_i32 m0, s41, 0x18600
	s_nop 0
	buffer_load_dwordx4 v250, s[8:11], s4 offen lds
	s_add_i32 m0, s41, 0x1a600
	s_nop 0
	buffer_load_dwordx4 v250, s[8:11], s4 offen offset:128 lds
	v_add_f32_e32 v145, v145, v242
	v_add_f32_e32 v145, v145, v243
	v_cvt_pk_bf16_f32 v233, v242, v243
	v_exp_f32_e32 v240, v88
	v_mfma_f32_32x32x16_bf16 v[112:127], v[104:107], v[136:139], v[112:127]
	ds_read_b128 v[104:107], v148 offset:37376
	ds_read_b64_tr_b16 v[200:201], v179 offset:27008
	ds_read_b64_tr_b16 v[202:203], v179 offset:27520
	v_exp_f32_e32 v241, v89
	v_add_f32_e32 v145, v145, v244
	v_add_f32_e32 v145, v145, v245
	v_cvt_pk_bf16_f32 v234, v244, v245
	v_exp_f32_e32 v242, v90
	v_mfma_f32_32x32x16_bf16 v[112:127], v[108:111], v[140:143], v[112:127]
	ds_read_b128 v[108:111], v149 offset:37376
	ds_read_b64_tr_b16 v[204:205], v179 offset:31168
	ds_read_b64_tr_b16 v[206:207], v179 offset:31680
	s_add_i32 m0, s43, 0x18600
	s_nop 0
	buffer_load_dwordx4 v251, s[12:15], s4 offen lds
	s_add_i32 m0, s43, 0x1a600
	s_nop 0
	buffer_load_dwordx4 v251, s[12:15], s4 offen offset:128 lds
	v_exp_f32_e32 v243, v91
	v_add_f32_e32 v145, v145, v246
	v_add_f32_e32 v145, v145, v247
	v_cvt_pk_bf16_f32 v235, v246, v247
	v_mfma_f32_32x32x16_bf16 v[32:47], v[208:211], v[228:231], v[32:47]
	ds_read_b64_tr_b16 v[208:209], v179 offset:19712
	ds_read_b64_tr_b16 v[210:211], v179 offset:20224
	v_exp_f32_e32 v244, v92
	v_exp_f32_e32 v245, v93
	v_add_f32_e32 v145, v145, v240
	v_add_f32_e32 v145, v145, v241
	v_mfma_f32_32x32x16_bf16 v[48:63], v[212:215], v[228:231], v[48:63]
	ds_read_b64_tr_b16 v[212:213], v179 offset:23872
	ds_read_b64_tr_b16 v[214:215], v179 offset:24384
	v_cvt_pk_bf16_f32 v236, v240, v241
	v_exp_f32_e32 v246, v94
	v_exp_f32_e32 v247, v95
	v_mfma_f32_32x32x16_bf16 v[16:31], v[216:219], v[228:231], v[16:31]
	ds_read_b64_tr_b16 v[216:217], v179 offset:28032
	ds_read_b64_tr_b16 v[218:219], v179 offset:28544
	v_add_f32_e32 v145, v145, v242
	v_add_f32_e32 v145, v145, v243
	v_cvt_pk_bf16_f32 v237, v242, v243
	v_add_f32_e32 v145, v145, v244
	v_add_f32_e32 v145, v145, v245
	v_cvt_pk_bf16_f32 v238, v244, v245
	v_mfma_f32_32x32x16_bf16 v[0:15], v[220:223], v[228:231], v[0:15]
	ds_read_b64_tr_b16 v[220:221], v179 offset:32192
	ds_read_b64_tr_b16 v[222:223], v179 offset:32704
	v_add_f32_e32 v145, v145, v246
	v_add_f32_e32 v249, v145, v247
	v_cvt_pk_bf16_f32 v239, v246, v247
	v_add_f32_e32 v249, v248, v249
	v_cmp_lt_f32_e32 vcc, s3, v249
	v_add_f32_e32 v191, v191, v249
	s_waitcnt vmcnt(4)
	s_barrier
	s_waitcnt lgkmcnt(8)
	v_mfma_f32_32x32x16_bf16 v[80:95], v[96:99], v[128:131], v[64:79]
	v_exp_f32_e32 v240, v112
	v_exp_f32_e32 v241, v113
	v_mfma_f32_32x32x16_bf16 v[80:95], v[100:103], v[132:135], v[80:95]
	v_exp_f32_e32 v242, v114
	v_exp_f32_e32 v243, v115
	v_exp_f32_e32 v244, v116
	v_mfma_f32_32x32x16_bf16 v[80:95], v[104:107], v[136:139], v[80:95]
	v_exp_f32_e32 v245, v117
	v_add_f32_e32 v145, v240, v241
	v_cvt_pk_bf16_f32 v224, v240, v241
	v_mfma_f32_32x32x16_bf16 v[80:95], v[108:111], v[140:143], v[80:95]
	v_exp_f32_e32 v246, v118
	v_exp_f32_e32 v247, v119
	v_mfma_f32_32x32x16_bf16 v[32:47], v[192:195], v[232:235], v[32:47]
	ds_read_b64_tr_b16 v[192:193], v180 offset:0
	ds_read_b64_tr_b16 v[194:195], v180 offset:512
	v_add_f32_e32 v145, v145, v242
	v_add_f32_e32 v145, v145, v243
	v_cvt_pk_bf16_f32 v225, v242, v243
	v_exp_f32_e32 v240, v120
	v_mfma_f32_32x32x16_bf16 v[48:63], v[196:199], v[232:235], v[48:63]
	ds_read_b64_tr_b16 v[196:197], v180 offset:4160
	ds_read_b64_tr_b16 v[198:199], v180 offset:4672
	v_exp_f32_e32 v241, v121
	v_add_f32_e32 v145, v145, v244
	v_add_f32_e32 v145, v145, v245
	v_cvt_pk_bf16_f32 v226, v244, v245
	v_mfma_f32_32x32x16_bf16 v[16:31], v[200:203], v[232:235], v[16:31]
	ds_read_b64_tr_b16 v[200:201], v180 offset:8320
	ds_read_b64_tr_b16 v[202:203], v180 offset:8832
	v_exp_f32_e32 v242, v122
	v_exp_f32_e32 v243, v123
	v_mfma_f32_32x32x16_bf16 v[0:15], v[204:207], v[232:235], v[0:15]
	ds_read_b64_tr_b16 v[204:205], v180 offset:12480
	ds_read_b64_tr_b16 v[206:207], v180 offset:12992
	v_add_f32_e32 v145, v145, v246
	v_add_f32_e32 v145, v145, v247
	v_cvt_pk_bf16_f32 v227, v246, v247
	v_exp_f32_e32 v244, v124
	s_waitcnt lgkmcnt(8)
	v_mfma_f32_32x32x16_bf16 v[32:47], v[208:211], v[236:239], v[32:47]
	ds_read_b64_tr_b16 v[208:209], v180 offset:1024
	ds_read_b64_tr_b16 v[210:211], v180 offset:1536
	v_exp_f32_e32 v245, v125
	v_add_f32_e32 v145, v145, v240
	v_add_f32_e32 v145, v145, v241
	v_mfma_f32_32x32x16_bf16 v[48:63], v[212:215], v[236:239], v[48:63]
	ds_read_b64_tr_b16 v[212:213], v180 offset:5184
	ds_read_b64_tr_b16 v[214:215], v180 offset:5696
	v_cvt_pk_bf16_f32 v228, v240, v241
	v_exp_f32_e32 v246, v126
	v_exp_f32_e32 v247, v127
	v_mfma_f32_32x32x16_bf16 v[16:31], v[216:219], v[236:239], v[16:31]
	ds_read_b64_tr_b16 v[216:217], v180 offset:9344
	ds_read_b64_tr_b16 v[218:219], v180 offset:9856
	v_add_f32_e32 v145, v145, v242
	v_add_f32_e32 v145, v145, v243
	v_cvt_pk_bf16_f32 v229, v242, v243
	v_add_f32_e32 v145, v145, v244
	v_mfma_f32_32x32x16_bf16 v[0:15], v[220:223], v[236:239], v[0:15]
	ds_read_b64_tr_b16 v[220:221], v180 offset:13504
	ds_read_b64_tr_b16 v[222:223], v180 offset:14016
	v_add_f32_e32 v145, v145, v245
	v_cvt_pk_bf16_f32 v230, v244, v245
	v_add_f32_e32 v145, v145, v246
	v_add_f32_e32 v248, v145, v247
	v_cvt_pk_bf16_f32 v231, v246, v247
	s_cbranch_vccz .Lb_contB0
	s_branch .Lb_rareB0
.Lb_contB0:
	s_waitcnt lgkmcnt(0)
	v_mfma_f32_32x32x16_bf16 v[32:47], v[192:195], v[224:227], v[32:47]
	v_mfma_f32_32x32x16_bf16 v[48:63], v[196:199], v[224:227], v[48:63]
	ds_read_b128 v[96:99], v150 offset:0
	ds_read_b128 v[100:103], v151 offset:0
	ds_read_b128 v[104:107], v152 offset:0
	ds_read_b128 v[108:111], v153 offset:0
	v_mfma_f32_32x32x16_bf16 v[16:31], v[200:203], v[224:227], v[16:31]
	v_exp_f32_e32 v240, v80
	v_exp_f32_e32 v241, v81
	v_exp_f32_e32 v242, v82
	v_mfma_f32_32x32x16_bf16 v[0:15], v[204:207], v[224:227], v[0:15]
	v_exp_f32_e32 v243, v83
	v_exp_f32_e32 v244, v84
	v_exp_f32_e32 v245, v85
	s_waitcnt lgkmcnt(0)
	v_mfma_f32_32x32x16_bf16 v[112:127], v[96:99], v[128:131], v[64:79]
	ds_read_b128 v[96:99], v150 offset:4096
	ds_read_b64_tr_b16 v[192:193], v180 offset:2048
	ds_read_b64_tr_b16 v[194:195], v180 offset:2560
	v_add_f32_e32 v145, v240, v241
	v_cvt_pk_bf16_f32 v232, v240, v241
	v_exp_f32_e32 v246, v86
	v_exp_f32_e32 v247, v87
	v_mfma_f32_32x32x16_bf16 v[112:127], v[100:103], v[132:135], v[112:127]
	ds_read_b128 v[100:103], v151 offset:4096
	ds_read_b64_tr_b16 v[196:197], v180 offset:6208
	ds_read_b64_tr_b16 v[198:199], v180 offset:6720
	s_cmp_gt_u32 s6, 59
	s_cbranch_scc1 .Lb_pn8
	s_and_b32 s0, s50, 0x1f8000
	s_lshl_b32 s4, s0, 1
	s_add_i32 m0, s41, 0x0
	s_nop 0
	buffer_load_dwordx4 v250, s[8:11], s4 offen lds
	s_branch .Lb_po8

.Lb_pn11:
	v_exp_f32_e32 v243, v91
	v_add_f32_e32 v145, v145, v246
	v_add_f32_e32 v145, v145, v247
	v_cvt_pk_bf16_f32 v235, v246, v247
	v_mfma_f32_32x32x16_bf16 v[32:47], v[208:211], v[228:231], v[32:47]
	ds_read_b64_tr_b16 v[208:209], v180 offset:3072
	ds_read_b64_tr_b16 v[210:211], v180 offset:3584
	v_exp_f32_e32 v244, v92
	v_exp_f32_e32 v245, v93
	v_add_f32_e32 v145, v145, v240
	v_add_f32_e32 v145, v145, v241
	v_mfma_f32_32x32x16_bf16 v[48:63], v[212:215], v[228:231], v[48:63]
	ds_read_b64_tr_b16 v[212:213], v180 offset:7232
	ds_read_b64_tr_b16 v[214:215], v180 offset:7744
	v_cvt_pk_bf16_f32 v236, v240, v241
	v_exp_f32_e32 v246, v94
	v_exp_f32_e32 v247, v95
	v_mfma_f32_32x32x16_bf16 v[16:31], v[216:219], v[228:231], v[16:31]
	ds_read_b64_tr_b16 v[216:217], v180 offset:11392
	ds_read_b64_tr_b16 v[218:219], v180 offset:11904
	v_add_f32_e32 v145, v145, v242
	v_add_f32_e32 v145, v145, v243
	v_cvt_pk_bf16_f32 v237, v242, v243
	v_add_f32_e32 v145, v145, v244
	v_add_f32_e32 v145, v145, v245
	v_cvt_pk_bf16_f32 v238, v244, v245
	v_mfma_f32_32x32x16_bf16 v[0:15], v[220:223], v[228:231], v[0:15]
	ds_read_b64_tr_b16 v[220:221], v180 offset:15552
	ds_read_b64_tr_b16 v[222:223], v180 offset:16064
	v_add_f32_e32 v145, v145, v246
	v_add_f32_e32 v249, v145, v247
	v_cvt_pk_bf16_f32 v239, v246, v247
	v_add_f32_e32 v249, v248, v249
	v_cmp_lt_f32_e32 vcc, s3, v249
	v_add_f32_e32 v191, v191, v249
	s_waitcnt vmcnt(4)
	s_barrier
	s_waitcnt lgkmcnt(8)
	v_mfma_f32_32x32x16_bf16 v[80:95], v[96:99], v[128:131], v[64:79]
	v_exp_f32_e32 v240, v112
	v_exp_f32_e32 v241, v113
	v_mfma_f32_32x32x16_bf16 v[80:95], v[100:103], v[132:135], v[80:95]
	v_exp_f32_e32 v242, v114
	v_exp_f32_e32 v243, v115
	v_exp_f32_e32 v244, v116
	v_mfma_f32_32x32x16_bf16 v[80:95], v[104:107], v[136:139], v[80:95]
	v_exp_f32_e32 v245, v117
	v_add_f32_e32 v145, v240, v241
	v_cvt_pk_bf16_f32 v224, v240, v241
	v_mfma_f32_32x32x16_bf16 v[80:95], v[108:111], v[140:143], v[80:95]
	v_exp_f32_e32 v246, v118
	v_exp_f32_e32 v247, v119
	v_mfma_f32_32x32x16_bf16 v[32:47], v[192:195], v[232:235], v[32:47]
	ds_read_b64_tr_b16 v[192:193], v182 offset:0
	ds_read_b64_tr_b16 v[194:195], v182 offset:512
	v_add_f32_e32 v145, v145, v242
	v_add_f32_e32 v145, v145, v243
	v_cvt_pk_bf16_f32 v225, v242, v243
	v_exp_f32_e32 v240, v120
	v_mfma_f32_32x32x16_bf16 v[48:63], v[196:199], v[232:235], v[48:63]
	ds_read_b64_tr_b16 v[196:197], v182 offset:4160
	ds_read_b64_tr_b16 v[198:199], v182 offset:4672
	v_exp_f32_e32 v241, v121
	v_add_f32_e32 v145, v145, v244
	v_add_f32_e32 v145, v145, v245
	v_cvt_pk_bf16_f32 v226, v244, v245
	v_mfma_f32_32x32x16_bf16 v[16:31], v[200:203], v[232:235], v[16:31]
	ds_read_b64_tr_b16 v[200:201], v182 offset:8320
	ds_read_b64_tr_b16 v[202:203], v182 offset:8832
	v_exp_f32_e32 v242, v122
	v_exp_f32_e32 v243, v123
	v_mfma_f32_32x32x16_bf16 v[0:15], v[204:207], v[232:235], v[0:15]
	ds_read_b64_tr_b16 v[204:205], v182 offset:12480
	ds_read_b64_tr_b16 v[206:207], v182 offset:12992
	v_add_f32_e32 v145, v145, v246
	v_add_f32_e32 v145, v145, v247
	v_cvt_pk_bf16_f32 v227, v246, v247
	v_exp_f32_e32 v244, v124
	s_waitcnt lgkmcnt(8)
	v_mfma_f32_32x32x16_bf16 v[32:47], v[208:211], v[236:239], v[32:47]
	ds_read_b64_tr_b16 v[208:209], v182 offset:1024
	ds_read_b64_tr_b16 v[210:211], v182 offset:1536
	v_exp_f32_e32 v245, v125
	v_add_f32_e32 v145, v145, v240
	v_add_f32_e32 v145, v145, v241
	v_mfma_f32_32x32x16_bf16 v[48:63], v[212:215], v[236:239], v[48:63]
	ds_read_b64_tr_b16 v[212:213], v182 offset:5184
	ds_read_b64_tr_b16 v[214:215], v182 offset:5696
	v_cvt_pk_bf16_f32 v228, v240, v241
	v_exp_f32_e32 v246, v126
	v_exp_f32_e32 v247, v127
	v_mfma_f32_32x32x16_bf16 v[16:31], v[216:219], v[236:239], v[16:31]
	ds_read_b64_tr_b16 v[216:217], v182 offset:9344
	ds_read_b64_tr_b16 v[218:219], v182 offset:9856
	v_add_f32_e32 v145, v145, v242
	v_add_f32_e32 v145, v145, v243
	v_cvt_pk_bf16_f32 v229, v242, v243
	v_add_f32_e32 v145, v145, v244
	v_mfma_f32_32x32x16_bf16 v[0:15], v[220:223], v[236:239], v[0:15]
	ds_read_b64_tr_b16 v[220:221], v182 offset:13504
	ds_read_b64_tr_b16 v[222:223], v182 offset:14016
	v_add_f32_e32 v145, v145, v245
	v_cvt_pk_bf16_f32 v230, v244, v245
	v_add_f32_e32 v145, v145, v246
	v_add_f32_e32 v248, v145, v247
	v_cvt_pk_bf16_f32 v231, v246, v247
	s_cbranch_vccz .Lb_contB1
	s_branch .Lb_rareB1
.Lb_contB1:
	s_waitcnt lgkmcnt(0)
	v_mfma_f32_32x32x16_bf16 v[32:47], v[192:195], v[224:227], v[32:47]
	v_mfma_f32_32x32x16_bf16 v[48:63], v[196:199], v[224:227], v[48:63]
	ds_read_b128 v[96:99], v150 offset:33280
	ds_read_b128 v[100:103], v151 offset:33280
	ds_read_b128 v[104:107], v152 offset:33280
	ds_read_b128 v[108:111], v153 offset:33280
	v_mfma_f32_32x32x16_bf16 v[16:31], v[200:203], v[224:227], v[16:31]
	v_exp_f32_e32 v240, v80
	v_exp_f32_e32 v241, v81
	v_exp_f32_e32 v242, v82
	v_mfma_f32_32x32x16_bf16 v[0:15], v[204:207], v[224:227], v[0:15]
	v_exp_f32_e32 v243, v83
	v_exp_f32_e32 v244, v84
	v_exp_f32_e32 v245, v85
	s_waitcnt lgkmcnt(0)
	v_mfma_f32_32x32x16_bf16 v[112:127], v[96:99], v[128:131], v[64:79]
	ds_read_b128 v[96:99], v150 offset:37376
	ds_read_b64_tr_b16 v[192:193], v182 offset:2048
	ds_read_b64_tr_b16 v[194:195], v182 offset:2560
	v_add_f32_e32 v145, v240, v241
	v_cvt_pk_bf16_f32 v232, v240, v241
	v_exp_f32_e32 v246, v86
	v_exp_f32_e32 v247, v87
	v_mfma_f32_32x32x16_bf16 v[112:127], v[100:103], v[132:135], v[112:127]
	ds_read_b128 v[100:103], v151 offset:37376
	ds_read_b64_tr_b16 v[196:197], v182 offset:6208
	ds_read_b64_tr_b16 v[198:199], v182 offset:6720
	s_cmp_gt_u32 s6, 59
	s_cbranch_scc1 .Lb_pn12
	s_add_i32 s0, s50, 0x8000
	s_and_b32 s0, s0, 0x1f8000
	s_lshl_b32 s4, s0, 1
	s_add_i32 m0, s41, 0x8200
	s_nop 0
	buffer_load_dwordx4 v250, s[8:11], s4 offen lds
	s_branch .Lb_po12

.Lb_pn15:
	v_exp_f32_e32 v243, v91
	v_add_f32_e32 v145, v145, v246
	v_add_f32_e32 v145, v145, v247
	v_cvt_pk_bf16_f32 v235, v246, v247
	v_mfma_f32_32x32x16_bf16 v[32:47], v[208:211], v[228:231], v[32:47]
	ds_read_b64_tr_b16 v[208:209], v182 offset:3072
	ds_read_b64_tr_b16 v[210:211], v182 offset:3584
	v_exp_f32_e32 v244, v92
	v_exp_f32_e32 v245, v93
	v_add_f32_e32 v145, v145, v240
	v_add_f32_e32 v145, v145, v241
	v_mfma_f32_32x32x16_bf16 v[48:63], v[212:215], v[228:231], v[48:63]
	ds_read_b64_tr_b16 v[212:213], v182 offset:7232
	ds_read_b64_tr_b16 v[214:215], v182 offset:7744
	v_cvt_pk_bf16_f32 v236, v240, v241
	v_exp_f32_e32 v246, v94
	v_exp_f32_e32 v247, v95
	v_mfma_f32_32x32x16_bf16 v[16:31], v[216:219], v[228:231], v[16:31]
	ds_read_b64_tr_b16 v[216:217], v182 offset:11392
	ds_read_b64_tr_b16 v[218:219], v182 offset:11904
	v_add_f32_e32 v145, v145, v242
	v_add_f32_e32 v145, v145, v243
	v_cvt_pk_bf16_f32 v237, v242, v243
	v_add_f32_e32 v145, v145, v244
	v_add_f32_e32 v145, v145, v245
	v_cvt_pk_bf16_f32 v238, v244, v245
	v_mfma_f32_32x32x16_bf16 v[0:15], v[220:223], v[228:231], v[0:15]
	ds_read_b64_tr_b16 v[220:221], v182 offset:15552
	ds_read_b64_tr_b16 v[222:223], v182 offset:16064
	v_add_f32_e32 v145, v145, v246
	v_add_f32_e32 v249, v145, v247
	v_cvt_pk_bf16_f32 v239, v246, v247
	v_add_f32_e32 v249, v248, v249
	v_cmp_lt_f32_e32 vcc, s3, v249
	v_add_f32_e32 v191, v191, v249
	s_waitcnt vmcnt(4)
	s_barrier
	s_waitcnt lgkmcnt(8)
	v_mfma_f32_32x32x16_bf16 v[80:95], v[96:99], v[128:131], v[64:79]
	v_exp_f32_e32 v240, v112
	v_exp_f32_e32 v241, v113
	v_mfma_f32_32x32x16_bf16 v[80:95], v[100:103], v[132:135], v[80:95]
	v_exp_f32_e32 v242, v114
	v_exp_f32_e32 v243, v115
	v_exp_f32_e32 v244, v116
	v_mfma_f32_32x32x16_bf16 v[80:95], v[104:107], v[136:139], v[80:95]
	v_exp_f32_e32 v245, v117
	v_add_f32_e32 v145, v240, v241
	v_cvt_pk_bf16_f32 v224, v240, v241
	v_mfma_f32_32x32x16_bf16 v[80:95], v[108:111], v[140:143], v[80:95]
	v_exp_f32_e32 v246, v118
	v_exp_f32_e32 v247, v119
	v_mfma_f32_32x32x16_bf16 v[32:47], v[192:195], v[232:235], v[32:47]
	ds_read_b64_tr_b16 v[192:193], v182 offset:33280
	ds_read_b64_tr_b16 v[194:195], v182 offset:33792
	v_add_f32_e32 v145, v145, v242
	v_add_f32_e32 v145, v145, v243
	v_cvt_pk_bf16_f32 v225, v242, v243
	v_exp_f32_e32 v240, v120
	v_mfma_f32_32x32x16_bf16 v[48:63], v[196:199], v[232:235], v[48:63]
	ds_read_b64_tr_b16 v[196:197], v182 offset:37440
	ds_read_b64_tr_b16 v[198:199], v182 offset:37952
	v_exp_f32_e32 v241, v121
	v_add_f32_e32 v145, v145, v244
	v_add_f32_e32 v145, v145, v245
	v_cvt_pk_bf16_f32 v226, v244, v245
	v_mfma_f32_32x32x16_bf16 v[16:31], v[200:203], v[232:235], v[16:31]
	ds_read_b64_tr_b16 v[200:201], v182 offset:41600
	ds_read_b64_tr_b16 v[202:203], v182 offset:42112
	v_exp_f32_e32 v242, v122
	v_exp_f32_e32 v243, v123
	v_mfma_f32_32x32x16_bf16 v[0:15], v[204:207], v[232:235], v[0:15]
	ds_read_b64_tr_b16 v[204:205], v182 offset:45760
	ds_read_b64_tr_b16 v[206:207], v182 offset:46272
	v_add_f32_e32 v145, v145, v246
	v_add_f32_e32 v145, v145, v247
	v_cvt_pk_bf16_f32 v227, v246, v247
	v_exp_f32_e32 v244, v124
	s_waitcnt lgkmcnt(8)
	v_mfma_f32_32x32x16_bf16 v[32:47], v[208:211], v[236:239], v[32:47]
	ds_read_b64_tr_b16 v[208:209], v182 offset:34304
	ds_read_b64_tr_b16 v[210:211], v182 offset:34816
	v_exp_f32_e32 v245, v125
	v_add_f32_e32 v145, v145, v240
	v_add_f32_e32 v145, v145, v241
	v_mfma_f32_32x32x16_bf16 v[48:63], v[212:215], v[236:239], v[48:63]
	ds_read_b64_tr_b16 v[212:213], v182 offset:38464
	ds_read_b64_tr_b16 v[214:215], v182 offset:38976
	v_cvt_pk_bf16_f32 v228, v240, v241
	v_exp_f32_e32 v246, v126
	v_exp_f32_e32 v247, v127
	v_mfma_f32_32x32x16_bf16 v[16:31], v[216:219], v[236:239], v[16:31]
	ds_read_b64_tr_b16 v[216:217], v182 offset:42624
	ds_read_b64_tr_b16 v[218:219], v182 offset:43136
	v_add_f32_e32 v145, v145, v242
	v_add_f32_e32 v145, v145, v243
	v_cvt_pk_bf16_f32 v229, v242, v243
	v_add_f32_e32 v145, v145, v244
	v_mfma_f32_32x32x16_bf16 v[0:15], v[220:223], v[236:239], v[0:15]
	ds_read_b64_tr_b16 v[220:221], v182 offset:46784
	ds_read_b64_tr_b16 v[222:223], v182 offset:47296
	v_add_f32_e32 v145, v145, v245
	v_cvt_pk_bf16_f32 v230, v244, v245
	v_add_f32_e32 v145, v145, v246
	v_add_f32_e32 v248, v145, v247
	v_cvt_pk_bf16_f32 v231, v246, v247
	s_cbranch_vccz .Lb_contB2
	s_branch .Lb_rareB2
.Lb_contB2:
	s_cmp_gt_u32 s6, 59
	s_cbranch_scc1 .Lb_final
	s_waitcnt lgkmcnt(0)
	v_mfma_f32_32x32x16_bf16 v[32:47], v[192:195], v[224:227], v[32:47]
	v_mfma_f32_32x32x16_bf16 v[48:63], v[196:199], v[224:227], v[48:63]
	ds_read_b128 v[96:99], v146 offset:0
	ds_read_b128 v[100:103], v147 offset:0
	ds_read_b128 v[104:107], v148 offset:0
	ds_read_b128 v[108:111], v149 offset:0
	v_mfma_f32_32x32x16_bf16 v[16:31], v[200:203], v[224:227], v[16:31]
	v_exp_f32_e32 v240, v80
	v_exp_f32_e32 v241, v81
	v_exp_f32_e32 v242, v82
	v_mfma_f32_32x32x16_bf16 v[0:15], v[204:207], v[224:227], v[0:15]
	v_exp_f32_e32 v243, v83
	v_exp_f32_e32 v244, v84
	v_exp_f32_e32 v245, v85
	s_waitcnt lgkmcnt(0)
	v_mfma_f32_32x32x16_bf16 v[112:127], v[96:99], v[128:131], v[64:79]
	ds_read_b128 v[96:99], v146 offset:4096
	ds_read_b64_tr_b16 v[192:193], v182 offset:35328
	ds_read_b64_tr_b16 v[194:195], v182 offset:35840
	v_add_f32_e32 v145, v240, v241
	v_cvt_pk_bf16_f32 v232, v240, v241
	v_exp_f32_e32 v246, v86
	v_exp_f32_e32 v247, v87
	v_mfma_f32_32x32x16_bf16 v[112:127], v[100:103], v[132:135], v[112:127]
	ds_read_b128 v[100:103], v147 offset:4096
	ds_read_b64_tr_b16 v[196:197], v182 offset:39488
	ds_read_b64_tr_b16 v[198:199], v182 offset:40000
	s_add_i32 s0, s50, 0x10000
	s_and_b32 s0, s0, 0x1f8000
	s_lshl_b32 s4, s0, 1
	s_add_i32 m0, s41, 0x10400
	s_nop 0
	buffer_load_dwordx4 v250, s[8:11], s4 offen lds
	s_add_i32 m0, s41, 0x12400
	s_nop 0
	buffer_load_dwordx4 v250, s[8:11], s4 offen offset:128 lds
	v_add_f32_e32 v145, v145, v242
	v_add_f32_e32 v145, v145, v243
	v_cvt_pk_bf16_f32 v233, v242, v243
	v_exp_f32_e32 v240, v88
	v_mfma_f32_32x32x16_bf16 v[112:127], v[104:107], v[136:139], v[112:127]
	ds_read_b128 v[104:107], v148 offset:4096
	ds_read_b64_tr_b16 v[200:201], v182 offset:43648
	ds_read_b64_tr_b16 v[202:203], v182 offset:44160
	v_exp_f32_e32 v241, v89
	v_add_f32_e32 v145, v145, v244
	v_add_f32_e32 v145, v145, v245
	v_cvt_pk_bf16_f32 v234, v244, v245
	v_exp_f32_e32 v242, v90
	v_mfma_f32_32x32x16_bf16 v[112:127], v[108:111], v[140:143], v[112:127]
	ds_read_b128 v[108:111], v149 offset:4096
	ds_read_b64_tr_b16 v[204:205], v182 offset:47808
	ds_read_b64_tr_b16 v[206:207], v182 offset:48320
	s_add_i32 m0, s43, 0x10400
	s_nop 0
	buffer_load_dwordx4 v251, s[12:15], s4 offen lds
	s_add_i32 m0, s43, 0x12400
	s_nop 0
	buffer_load_dwordx4 v251, s[12:15], s4 offen offset:128 lds
	v_exp_f32_e32 v243, v91
	v_add_f32_e32 v145, v145, v246
	v_add_f32_e32 v145, v145, v247
	v_cvt_pk_bf16_f32 v235, v246, v247
	v_mfma_f32_32x32x16_bf16 v[32:47], v[208:211], v[228:231], v[32:47]
	ds_read_b64_tr_b16 v[208:209], v182 offset:36352
	ds_read_b64_tr_b16 v[210:211], v182 offset:36864
	v_exp_f32_e32 v244, v92
	v_exp_f32_e32 v245, v93
	v_add_f32_e32 v145, v145, v240
	v_add_f32_e32 v145, v145, v241
	v_mfma_f32_32x32x16_bf16 v[48:63], v[212:215], v[228:231], v[48:63]
	ds_read_b64_tr_b16 v[212:213], v182 offset:40512
	ds_read_b64_tr_b16 v[214:215], v182 offset:41024
	v_cvt_pk_bf16_f32 v236, v240, v241
	v_exp_f32_e32 v246, v94
	v_exp_f32_e32 v247, v95
	v_mfma_f32_32x32x16_bf16 v[16:31], v[216:219], v[228:231], v[16:31]
	ds_read_b64_tr_b16 v[216:217], v182 offset:44672
	ds_read_b64_tr_b16 v[218:219], v182 offset:45184
	v_add_f32_e32 v145, v145, v242
	v_add_f32_e32 v145, v145, v243
	v_cvt_pk_bf16_f32 v237, v242, v243
	v_add_f32_e32 v145, v145, v244
	v_add_f32_e32 v145, v145, v245
	v_cvt_pk_bf16_f32 v238, v244, v245
	v_mfma_f32_32x32x16_bf16 v[0:15], v[220:223], v[228:231], v[0:15]
	ds_read_b64_tr_b16 v[220:221], v182 offset:48832
	ds_read_b64_tr_b16 v[222:223], v182 offset:49344
	v_add_f32_e32 v145, v145, v246
	v_add_f32_e32 v249, v145, v247
	v_cvt_pk_bf16_f32 v239, v246, v247
	v_add_f32_e32 v249, v248, v249
	v_cmp_lt_f32_e32 vcc, s3, v249
	v_add_f32_e32 v191, v191, v249
	s_waitcnt vmcnt(4)
	s_barrier
	s_waitcnt lgkmcnt(8)
	v_mfma_f32_32x32x16_bf16 v[80:95], v[96:99], v[128:131], v[64:79]
	v_exp_f32_e32 v240, v112
	v_exp_f32_e32 v241, v113
	v_mfma_f32_32x32x16_bf16 v[80:95], v[100:103], v[132:135], v[80:95]
	v_exp_f32_e32 v242, v114
	v_exp_f32_e32 v243, v115
	v_exp_f32_e32 v244, v116
	v_mfma_f32_32x32x16_bf16 v[80:95], v[104:107], v[136:139], v[80:95]
	v_exp_f32_e32 v245, v117
	v_add_f32_e32 v145, v240, v241
	v_cvt_pk_bf16_f32 v224, v240, v241
	v_mfma_f32_32x32x16_bf16 v[80:95], v[108:111], v[140:143], v[80:95]
	v_exp_f32_e32 v246, v118
	v_exp_f32_e32 v247, v119
	v_mfma_f32_32x32x16_bf16 v[32:47], v[192:195], v[232:235], v[32:47]
	ds_read_b64_tr_b16 v[192:193], v179 offset:16640
	ds_read_b64_tr_b16 v[194:195], v179 offset:17152
	v_add_f32_e32 v145, v145, v242
	v_add_f32_e32 v145, v145, v243
	v_cvt_pk_bf16_f32 v225, v242, v243
	v_exp_f32_e32 v240, v120
	v_mfma_f32_32x32x16_bf16 v[48:63], v[196:199], v[232:235], v[48:63]
	ds_read_b64_tr_b16 v[196:197], v179 offset:20800
	ds_read_b64_tr_b16 v[198:199], v179 offset:21312
	v_exp_f32_e32 v241, v121
	v_add_f32_e32 v145, v145, v244
	v_add_f32_e32 v145, v145, v245
	v_cvt_pk_bf16_f32 v226, v244, v245
	v_mfma_f32_32x32x16_bf16 v[16:31], v[200:203], v[232:235], v[16:31]
	ds_read_b64_tr_b16 v[200:201], v179 offset:24960
	ds_read_b64_tr_b16 v[202:203], v179 offset:25472
	v_exp_f32_e32 v242, v122
	v_exp_f32_e32 v243, v123
	v_mfma_f32_32x32x16_bf16 v[0:15], v[204:207], v[232:235], v[0:15]
	ds_read_b64_tr_b16 v[204:205], v179 offset:29120
	ds_read_b64_tr_b16 v[206:207], v179 offset:29632
	v_add_f32_e32 v145, v145, v246
	v_add_f32_e32 v145, v145, v247
	v_cvt_pk_bf16_f32 v227, v246, v247
	v_exp_f32_e32 v244, v124
	s_waitcnt lgkmcnt(8)
	v_mfma_f32_32x32x16_bf16 v[32:47], v[208:211], v[236:239], v[32:47]
	ds_read_b64_tr_b16 v[208:209], v179 offset:17664
	ds_read_b64_tr_b16 v[210:211], v179 offset:18176
	v_exp_f32_e32 v245, v125
	v_add_f32_e32 v145, v145, v240
	v_add_f32_e32 v145, v145, v241
	v_mfma_f32_32x32x16_bf16 v[48:63], v[212:215], v[236:239], v[48:63]
	ds_read_b64_tr_b16 v[212:213], v179 offset:21824
	ds_read_b64_tr_b16 v[214:215], v179 offset:22336
	v_cvt_pk_bf16_f32 v228, v240, v241
	v_exp_f32_e32 v246, v126
	v_exp_f32_e32 v247, v127
	v_mfma_f32_32x32x16_bf16 v[16:31], v[216:219], v[236:239], v[16:31]
	ds_read_b64_tr_b16 v[216:217], v179 offset:25984
	ds_read_b64_tr_b16 v[218:219], v179 offset:26496
	v_add_f32_e32 v145, v145, v242
	v_add_f32_e32 v145, v145, v243
	v_cvt_pk_bf16_f32 v229, v242, v243
	v_add_f32_e32 v145, v145, v244
	v_mfma_f32_32x32x16_bf16 v[0:15], v[220:223], v[236:239], v[0:15]
	ds_read_b64_tr_b16 v[220:221], v179 offset:30144
	ds_read_b64_tr_b16 v[222:223], v179 offset:30656
	v_add_f32_e32 v145, v145, v245
	v_cvt_pk_bf16_f32 v230, v244, v245
	v_add_f32_e32 v145, v145, v246
	v_add_f32_e32 v248, v145, v247
	v_cvt_pk_bf16_f32 v231, v246, v247
	s_cbranch_vccz .Lb_contB3
	s_branch .Lb_rareB3
.Lb_contB3:
	s_add_i32 s6, s6, 4
	s_add_i32 s50, s50, 0x20000
	s_branch .Lb_loopB
